# softmax epilogue: the eight serialized row-statistics loads issued together (as done for SwiGLU/in-proj)
# speedup vs baseline: 1.0197x; 1.0130x over previous
.LBB0_987:
	v_mov_b32_e32 v148, v218
	s_lshl_b32 s17, s26, 8
	v_and_b32_e32 v149, 15, v148
	v_or_b32_e32 v206, s43, v149
	v_add_u32_e32 v142, s17, v206
	v_ashrrev_i32_e32 v143, 31, v142
	v_lshl_add_u64 v[144:145], v[142:143], 3, s[12:13]
	global_load_dwordx2 v[146:147], v[144:145], off
	global_load_dwordx2 v[196:197], v[144:145], off offset:128
	global_load_dwordx2 v[198:199], v[144:145], off offset:256
	global_load_dwordx2 v[216:217], v[144:145], off offset:384
	global_load_dwordx2 v[220:221], v[144:145], off offset:1024
	global_load_dwordx2 v[222:223], v[144:145], off offset:1152
	global_load_dwordx2 v[210:211], v[144:145], off offset:1280
	global_load_dwordx2 v[212:213], v[144:145], off offset:1408
	v_bfe_u32 v207, v148, 4, 2
	v_lshlrev_b32_e32 v148, 2, v149
	s_waitcnt vmcnt(0)
	v_ffbh_u32_e32 v150, v147
	v_min_u32_e32 v150, 32, v150
	v_lshlrev_b64 v[146:147], v150, v[146:147]
	v_min_u32_e32 v146, 1, v146
	v_or_b32_e32 v146, v147, v146
	v_cvt_f32_u32_e32 v146, v146
	v_sub_u32_e32 v147, 32, v150
	v_ldexp_f32 v146, v146, v147
	v_fmamk_f32 v146, v146, 0x31800000, v219
	v_mul_f32_e32 v147, 0x4b800000, v146
	v_cmp_gt_f32_e32 vcc, s86, v146
	s_nop 1
	v_cndmask_b32_e32 v146, v146, v147, vcc
	v_rsq_f32_e32 v146, v146
	v_lshlrev_b32_e32 v147, 6, v207
	v_bitop3_b32 v208, v147, 64, v148 bitop3:0x36
	v_bitop3_b32 v209, v147, s82, v148 bitop3:0x36
	v_mul_f32_e32 v149, 0x45800000, v146
	v_cndmask_b32_e32 v146, v146, v149, vcc
	v_mul_f32_e32 v146, 0x3db8aa3b, v146
	v_pk_mul_f32 v[128:129], v[128:129], v[146:147] op_sel_hi:[1,0]
	v_pk_mul_f32 v[126:127], v[126:127], v[146:147] op_sel_hi:[1,0]
	v_pk_mul_f32 v[124:125], v[124:125], v[146:147] op_sel_hi:[1,0]
	v_pk_mul_f32 v[122:123], v[122:123], v[146:147] op_sel_hi:[1,0]
	v_pk_mul_f32 v[120:121], v[120:121], v[146:147] op_sel_hi:[1,0]
	v_pk_mul_f32 v[118:119], v[118:119], v[146:147] op_sel_hi:[1,0]
	v_pk_mul_f32 v[116:117], v[116:117], v[146:147] op_sel_hi:[1,0]
	v_pk_mul_f32 v[114:115], v[114:115], v[146:147] op_sel_hi:[1,0]
	v_max_f32_e32 v146, v126, v127
	v_max_f32_e32 v149, v128, v129
	v_max_f32_e32 v150, v122, v123
	v_max_f32_e32 v151, v124, v125
	v_max3_f32 v146, v146, s61, v149
	v_max_f32_e32 v152, v118, v119
	v_max_f32_e32 v153, v120, v121
	v_max3_f32 v146, v146, v150, v151
	v_max_f32_e32 v154, v114, v115
	v_max3_f32 v146, v146, v152, v153
	v_max_f32_e32 v149, v116, v117
	v_max3_f32 v146, v146, v154, v149
	ds_bpermute_b32 v149, v208, v146
	v_cmp_eq_u32_e32 vcc, 0, v207
	s_waitcnt lgkmcnt(0)
	v_max_f32_e32 v147, v149, v149
	v_max_f32_e32 v146, v146, v147
	ds_bpermute_b32 v147, v209, v146
	s_and_saveexec_b64 s[4:5], vcc
	s_cbranch_execz .LBB0_989
	s_waitcnt lgkmcnt(0)
	v_max_f32_e32 v147, v147, v147
	v_max_f32_e32 v146, v146, v146
	v_lshl_add_u32 v148, v206, 4, s50
	v_max_f32_e32 v146, v146, v147
	ds_write_b32 v148, v146
.LBB0_989:
	s_or_b64 exec, exec, s[4:5]
	s_waitcnt lgkmcnt(0)
	v_mov_b64_e32 v[146:147], v[196:197]
	v_or_b32_e32 v205, 16, v206
	s_nop 0
	v_ffbh_u32_e32 v148, v147
	v_min_u32_e32 v148, 32, v148
	v_lshlrev_b64 v[146:147], v148, v[146:147]
	v_min_u32_e32 v146, 1, v146
	v_or_b32_e32 v146, v147, v146
	v_cvt_f32_u32_e32 v146, v146
	v_sub_u32_e32 v147, 32, v148
	v_ldexp_f32 v146, v146, v147
	v_fmamk_f32 v146, v146, 0x31800000, v219
	v_cmp_gt_f32_e64 s[4:5], s86, v146
	v_mul_f32_e32 v147, 0x4b800000, v146
	s_nop 0
	v_cndmask_b32_e64 v146, v146, v147, s[4:5]
	v_rsq_f32_e32 v146, v146
	s_nop 0
	v_mul_f32_e32 v147, 0x45800000, v146
	v_cndmask_b32_e64 v146, v146, v147, s[4:5]
	v_mul_f32_e32 v146, 0x3db8aa3b, v146
	v_pk_mul_f32 v[112:113], v[112:113], v[146:147] op_sel_hi:[1,0]
	v_pk_mul_f32 v[110:111], v[110:111], v[146:147] op_sel_hi:[1,0]
	v_max_f32_e32 v148, v112, v113
	v_max_f32_e32 v147, v110, v111
	v_max3_f32 v147, v147, s61, v148
	v_pk_mul_f32 v[108:109], v[108:109], v[146:147] op_sel_hi:[1,0]
	v_pk_mul_f32 v[106:107], v[106:107], v[146:147] op_sel_hi:[1,0]
	v_max_f32_e32 v149, v108, v109
	v_max_f32_e32 v148, v106, v107
	v_max3_f32 v147, v147, v148, v149
	v_pk_mul_f32 v[104:105], v[104:105], v[146:147] op_sel_hi:[1,0]
	v_pk_mul_f32 v[102:103], v[102:103], v[146:147] op_sel_hi:[1,0]
	v_max_f32_e32 v149, v104, v105
	v_max_f32_e32 v148, v102, v103
	v_max3_f32 v147, v147, v148, v149
	v_pk_mul_f32 v[100:101], v[100:101], v[146:147] op_sel_hi:[1,0]
	v_pk_mul_f32 v[98:99], v[98:99], v[146:147] op_sel_hi:[1,0]
	v_max_f32_e32 v148, v100, v101
	v_max_f32_e32 v146, v98, v99
	v_max3_f32 v146, v147, v146, v148
	ds_bpermute_b32 v147, v208, v146
	s_waitcnt lgkmcnt(0)
	v_max_f32_e32 v147, v147, v147
	v_max_f32_e32 v146, v146, v147
	ds_bpermute_b32 v147, v209, v146
	s_and_saveexec_b64 s[4:5], vcc
	s_cbranch_execz .LBB0_991
	s_waitcnt lgkmcnt(0)
	v_max_f32_e32 v147, v147, v147
	v_max_f32_e32 v146, v146, v146
	v_lshl_add_u32 v148, v205, 4, s50
	v_max_f32_e32 v146, v146, v147
	ds_write_b32 v148, v146
.LBB0_991:
	s_or_b64 exec, exec, s[4:5]
	s_waitcnt lgkmcnt(0)
	v_mov_b64_e32 v[146:147], v[198:199]
	v_or_b32_e32 v204, 32, v206
	s_nop 0
	v_ffbh_u32_e32 v148, v147
	v_min_u32_e32 v148, 32, v148
	v_lshlrev_b64 v[146:147], v148, v[146:147]
	v_min_u32_e32 v146, 1, v146
	v_or_b32_e32 v146, v147, v146
	v_cvt_f32_u32_e32 v146, v146
	v_sub_u32_e32 v147, 32, v148
	v_ldexp_f32 v146, v146, v147
	v_fmamk_f32 v146, v146, 0x31800000, v219
	v_cmp_gt_f32_e64 s[4:5], s86, v146
	v_mul_f32_e32 v147, 0x4b800000, v146
	s_nop 0
	v_cndmask_b32_e64 v146, v146, v147, s[4:5]
	v_rsq_f32_e32 v146, v146
	s_nop 0
	v_mul_f32_e32 v147, 0x45800000, v146
	v_cndmask_b32_e64 v146, v146, v147, s[4:5]
	v_mul_f32_e32 v146, 0x3db8aa3b, v146
	v_pk_mul_f32 v[96:97], v[96:97], v[146:147] op_sel_hi:[1,0]
	v_pk_mul_f32 v[94:95], v[94:95], v[146:147] op_sel_hi:[1,0]
	v_max_f32_e32 v148, v96, v97
	v_max_f32_e32 v147, v94, v95
	v_max3_f32 v147, v147, s61, v148
	v_pk_mul_f32 v[92:93], v[92:93], v[146:147] op_sel_hi:[1,0]
	v_pk_mul_f32 v[90:91], v[90:91], v[146:147] op_sel_hi:[1,0]
	v_max_f32_e32 v149, v92, v93
	v_max_f32_e32 v148, v90, v91
	v_max3_f32 v147, v147, v148, v149
	v_pk_mul_f32 v[88:89], v[88:89], v[146:147] op_sel_hi:[1,0]
	v_pk_mul_f32 v[86:87], v[86:87], v[146:147] op_sel_hi:[1,0]
	v_max_f32_e32 v149, v88, v89
	v_max_f32_e32 v148, v86, v87
	v_max3_f32 v147, v147, v148, v149
	v_pk_mul_f32 v[84:85], v[84:85], v[146:147] op_sel_hi:[1,0]
	v_pk_mul_f32 v[82:83], v[82:83], v[146:147] op_sel_hi:[1,0]
	v_max_f32_e32 v148, v84, v85
	v_max_f32_e32 v146, v82, v83
	v_max3_f32 v146, v147, v146, v148
	ds_bpermute_b32 v147, v208, v146
	s_waitcnt lgkmcnt(0)
	v_max_f32_e32 v147, v147, v147
	v_max_f32_e32 v146, v146, v147
	ds_bpermute_b32 v147, v209, v146
	s_and_saveexec_b64 s[4:5], vcc
	s_cbranch_execz .LBB0_993
	s_waitcnt lgkmcnt(0)
	v_max_f32_e32 v147, v147, v147
	v_max_f32_e32 v146, v146, v146
	v_lshl_add_u32 v148, v204, 4, s50
	v_max_f32_e32 v146, v146, v147
	ds_write_b32 v148, v146
.LBB0_993:
	s_or_b64 exec, exec, s[4:5]
	s_waitcnt lgkmcnt(0)
	v_mov_b64_e32 v[146:147], v[216:217]
	v_or_b32_e32 v195, 48, v206
	s_nop 0
	v_ffbh_u32_e32 v148, v147
	v_min_u32_e32 v148, 32, v148
	v_lshlrev_b64 v[146:147], v148, v[146:147]
	v_min_u32_e32 v146, 1, v146
	v_or_b32_e32 v146, v147, v146
	v_cvt_f32_u32_e32 v146, v146
	v_sub_u32_e32 v147, 32, v148
	v_ldexp_f32 v146, v146, v147
	v_fmamk_f32 v146, v146, 0x31800000, v219
	v_cmp_gt_f32_e64 s[4:5], s86, v146
	v_mul_f32_e32 v147, 0x4b800000, v146
	s_nop 0
	v_cndmask_b32_e64 v146, v146, v147, s[4:5]
	v_rsq_f32_e32 v146, v146
	s_nop 0
	v_mul_f32_e32 v147, 0x45800000, v146
	v_cndmask_b32_e64 v146, v146, v147, s[4:5]
	v_mul_f32_e32 v148, 0x3db8aa3b, v146
	v_pk_mul_f32 v[80:81], v[80:81], v[148:149] op_sel_hi:[1,0]
	v_pk_mul_f32 v[78:79], v[78:79], v[148:149] op_sel_hi:[1,0]
	v_max_f32_e32 v147, v80, v81
	v_max_f32_e32 v146, v78, v79
	v_pk_mul_f32 v[76:77], v[76:77], v[148:149] op_sel_hi:[1,0]
	v_pk_mul_f32 v[74:75], v[74:75], v[148:149] op_sel_hi:[1,0]
	v_max3_f32 v146, v146, s61, v147
	v_max_f32_e32 v147, v74, v75
	v_max_f32_e32 v149, v76, v77
	v_max3_f32 v149, v146, v147, v149
	v_pk_mul_f32 v[72:73], v[72:73], v[148:149] op_sel_hi:[1,0]
	v_pk_mul_f32 v[146:147], v[70:71], v[148:149] op_sel_hi:[1,0]
	v_max_f32_e32 v71, v72, v73
	v_max_f32_e32 v70, v146, v147
	v_max3_f32 v150, v149, v70, v71
	v_pk_mul_f32 v[70:71], v[68:69], v[148:149] op_sel_hi:[1,0]
	v_pk_mul_f32 v[148:149], v[66:67], v[148:149] op_sel_hi:[1,0]
	v_max_f32_e32 v67, v70, v71
	v_max_f32_e32 v66, v148, v149
	v_max3_f32 v66, v150, v66, v67
	ds_bpermute_b32 v67, v208, v66
	s_waitcnt lgkmcnt(0)
	v_max_f32_e32 v67, v67, v67
	v_max_f32_e32 v66, v66, v67
	ds_bpermute_b32 v67, v209, v66
	s_and_saveexec_b64 s[4:5], vcc
	s_cbranch_execz .LBB0_995
	s_waitcnt lgkmcnt(0)
	v_max_f32_e32 v67, v67, v67
	v_max_f32_e32 v66, v66, v66
	v_lshl_add_u32 v68, v195, 4, s50
	v_max_f32_e32 v66, v66, v67
	ds_write_b32 v68, v66
.LBB0_995:
	s_or_b64 exec, exec, s[4:5]
	s_waitcnt lgkmcnt(0)
	v_mov_b64_e32 v[66:67], v[220:221]
	v_add_u32_e32 v194, 0x80, v206
	s_nop 0
	v_ffbh_u32_e32 v68, v67
	v_min_u32_e32 v68, 32, v68
	v_lshlrev_b64 v[66:67], v68, v[66:67]
	v_min_u32_e32 v66, 1, v66
	v_or_b32_e32 v66, v67, v66
	v_cvt_f32_u32_e32 v66, v66
	v_sub_u32_e32 v67, 32, v68
	v_ldexp_f32 v66, v66, v67
	v_fmamk_f32 v66, v66, 0x31800000, v219
	v_cmp_gt_f32_e64 s[4:5], s86, v66
	v_mul_f32_e32 v67, 0x4b800000, v66
	s_nop 0
	v_cndmask_b32_e64 v66, v66, v67, s[4:5]
	v_rsq_f32_e32 v66, v66
	s_nop 0
	v_mul_f32_e32 v67, 0x45800000, v66
	v_cndmask_b32_e64 v66, v66, v67, s[4:5]
	v_mul_f32_e32 v66, 0x3db8aa3b, v66
	v_pk_mul_f32 v[150:151], v[64:65], v[66:67] op_sel_hi:[1,0]
	v_pk_mul_f32 v[62:63], v[62:63], v[66:67] op_sel_hi:[1,0]
	v_max_f32_e32 v65, v150, v151
	v_max_f32_e32 v64, v62, v63
	v_pk_mul_f32 v[152:153], v[60:61], v[66:67] op_sel_hi:[1,0]
	v_pk_mul_f32 v[154:155], v[58:59], v[66:67] op_sel_hi:[1,0]
	v_max3_f32 v64, v64, s61, v65
	v_max_f32_e32 v58, v154, v155
	v_max_f32_e32 v59, v152, v153
	v_pk_mul_f32 v[56:57], v[56:57], v[66:67] op_sel_hi:[1,0]
	v_pk_mul_f32 v[54:55], v[54:55], v[66:67] op_sel_hi:[1,0]
	v_max3_f32 v58, v64, v58, v59
	v_max_f32_e32 v59, v54, v55
	v_max_f32_e32 v60, v56, v57
	v_pk_mul_f32 v[52:53], v[52:53], v[66:67] op_sel_hi:[1,0]
	v_pk_mul_f32 v[50:51], v[50:51], v[66:67] op_sel_hi:[1,0]
	v_max3_f32 v58, v58, v59, v60
	v_max_f32_e32 v59, v50, v51
	v_max_f32_e32 v60, v52, v53
	v_max3_f32 v58, v58, v59, v60
	ds_bpermute_b32 v59, v208, v58
	s_waitcnt lgkmcnt(0)
	v_max_f32_e32 v59, v59, v59
	v_max_f32_e32 v58, v58, v59
	ds_bpermute_b32 v59, v209, v58
	s_and_saveexec_b64 s[4:5], vcc
	s_cbranch_execz .LBB0_997
	s_waitcnt lgkmcnt(0)
	v_max_f32_e32 v59, v59, v59
	v_max_f32_e32 v58, v58, v58
	v_lshl_add_u32 v60, v194, 4, s50
	v_max_f32_e32 v58, v58, v59
	ds_write_b32 v60, v58
.LBB0_997:
	s_or_b64 exec, exec, s[4:5]
	s_waitcnt lgkmcnt(0)
	v_mov_b64_e32 v[58:59], v[222:223]
	v_add_u32_e32 v193, 0x90, v206
	s_nop 0
	v_ffbh_u32_e32 v60, v59
	v_min_u32_e32 v60, 32, v60
	v_lshlrev_b64 v[58:59], v60, v[58:59]
	v_min_u32_e32 v58, 1, v58
	v_or_b32_e32 v58, v59, v58
	v_cvt_f32_u32_e32 v58, v58
	v_sub_u32_e32 v59, 32, v60
	v_ldexp_f32 v58, v58, v59
	v_fmamk_f32 v58, v58, 0x31800000, v219
	v_cmp_gt_f32_e64 s[4:5], s86, v58
	v_mul_f32_e32 v59, 0x4b800000, v58
	s_nop 0
	v_cndmask_b32_e64 v58, v58, v59, s[4:5]
	v_rsq_f32_e32 v58, v58
	s_nop 0
	v_mul_f32_e32 v59, 0x45800000, v58
	v_cndmask_b32_e64 v58, v58, v59, s[4:5]
	v_mul_f32_e32 v58, 0x3db8aa3b, v58
	v_pk_mul_f32 v[48:49], v[48:49], v[58:59] op_sel_hi:[1,0]
	v_pk_mul_f32 v[46:47], v[46:47], v[58:59] op_sel_hi:[1,0]
	v_max_f32_e32 v60, v48, v49
	v_max_f32_e32 v59, v46, v47
	v_max3_f32 v59, v59, s61, v60
	v_pk_mul_f32 v[44:45], v[44:45], v[58:59] op_sel_hi:[1,0]
	v_pk_mul_f32 v[42:43], v[42:43], v[58:59] op_sel_hi:[1,0]
	v_max_f32_e32 v61, v44, v45
	v_max_f32_e32 v60, v42, v43
	v_max3_f32 v59, v59, v60, v61
	v_pk_mul_f32 v[40:41], v[40:41], v[58:59] op_sel_hi:[1,0]
	v_pk_mul_f32 v[158:159], v[38:39], v[58:59] op_sel_hi:[1,0]
	v_max_f32_e32 v39, v40, v41
	v_max_f32_e32 v38, v158, v159
	v_pk_mul_f32 v[156:157], v[36:37], v[58:59] op_sel_hi:[1,0]
	v_pk_mul_f32 v[34:35], v[34:35], v[58:59] op_sel_hi:[1,0]
	v_max3_f32 v38, v59, v38, v39
	v_max_f32_e32 v36, v34, v35
	v_max_f32_e32 v37, v156, v157
	v_max3_f32 v36, v38, v36, v37
	ds_bpermute_b32 v37, v208, v36
	s_waitcnt lgkmcnt(0)
	v_max_f32_e32 v37, v37, v37
	v_max_f32_e32 v36, v36, v37
	ds_bpermute_b32 v37, v209, v36
	s_and_saveexec_b64 s[4:5], vcc
	s_cbranch_execz .LBB0_999
	s_waitcnt lgkmcnt(0)
	v_max_f32_e32 v37, v37, v37
	v_max_f32_e32 v36, v36, v36
	v_lshl_add_u32 v38, v193, 4, s50
	v_max_f32_e32 v36, v36, v37
	ds_write_b32 v38, v36
.LBB0_999:
	s_or_b64 exec, exec, s[4:5]
	s_waitcnt lgkmcnt(0)
	v_mov_b64_e32 v[36:37], v[210:211]
	v_add_u32_e32 v192, 0xa0, v206
	s_nop 0
	v_ffbh_u32_e32 v38, v37
	v_min_u32_e32 v38, 32, v38
	v_lshlrev_b64 v[36:37], v38, v[36:37]
	v_min_u32_e32 v36, 1, v36
	v_or_b32_e32 v36, v37, v36
	v_cvt_f32_u32_e32 v36, v36
	v_sub_u32_e32 v37, 32, v38
	v_ldexp_f32 v36, v36, v37
	v_fmamk_f32 v36, v36, 0x31800000, v219
	v_cmp_gt_f32_e64 s[4:5], s86, v36
	v_mul_f32_e32 v37, 0x4b800000, v36
	s_nop 0
	v_cndmask_b32_e64 v36, v36, v37, s[4:5]
	v_rsq_f32_e32 v36, v36
	s_nop 0
	v_mul_f32_e32 v37, 0x45800000, v36
	v_cndmask_b32_e64 v36, v36, v37, s[4:5]
	v_mul_f32_e32 v36, 0x3db8aa3b, v36
	v_pk_mul_f32 v[160:161], v[32:33], v[36:37] op_sel_hi:[1,0]
	v_pk_mul_f32 v[166:167], v[30:31], v[36:37] op_sel_hi:[1,0]
	v_max_f32_e32 v31, v160, v161
	v_max_f32_e32 v30, v166, v167
	v_pk_mul_f32 v[162:163], v[28:29], v[36:37] op_sel_hi:[1,0]
	v_pk_mul_f32 v[168:169], v[26:27], v[36:37] op_sel_hi:[1,0]
	v_max3_f32 v30, v30, s61, v31
	v_max_f32_e32 v26, v168, v169
	v_max_f32_e32 v27, v162, v163
	v_pk_mul_f32 v[164:165], v[24:25], v[36:37] op_sel_hi:[1,0]
	v_pk_mul_f32 v[170:171], v[22:23], v[36:37] op_sel_hi:[1,0]
	v_max3_f32 v26, v30, v26, v27
	v_max_f32_e32 v22, v170, v171
	v_max_f32_e32 v23, v164, v165
	v_pk_mul_f32 v[20:21], v[20:21], v[36:37] op_sel_hi:[1,0]
	v_pk_mul_f32 v[18:19], v[18:19], v[36:37] op_sel_hi:[1,0]
	v_max3_f32 v22, v26, v22, v23
	v_max_f32_e32 v23, v18, v19
	v_max_f32_e32 v24, v20, v21
	v_max3_f32 v22, v22, v23, v24
	ds_bpermute_b32 v23, v208, v22
	s_waitcnt lgkmcnt(0)
	v_max_f32_e32 v23, v23, v23
	v_max_f32_e32 v22, v22, v23
	ds_bpermute_b32 v23, v209, v22
	s_and_saveexec_b64 s[4:5], vcc
	s_cbranch_execz .LBB0_1001
	s_waitcnt lgkmcnt(0)
	v_max_f32_e32 v23, v23, v23
	v_max_f32_e32 v22, v22, v22
	v_lshl_add_u32 v24, v192, 4, s50
	v_max_f32_e32 v22, v22, v23
	ds_write_b32 v24, v22
.LBB0_1001:
	s_or_b64 exec, exec, s[4:5]
	s_waitcnt lgkmcnt(0)
	v_mov_b64_e32 v[22:23], v[212:213]
	v_add_u32_e32 v191, 0xb0, v206
	s_nop 0
	v_ffbh_u32_e32 v24, v23
	v_min_u32_e32 v24, 32, v24
	v_lshlrev_b64 v[22:23], v24, v[22:23]
	v_min_u32_e32 v22, 1, v22
	v_or_b32_e32 v22, v23, v22
	v_cvt_f32_u32_e32 v22, v22
	v_sub_u32_e32 v23, 32, v24
	v_ldexp_f32 v22, v22, v23
	v_fmamk_f32 v22, v22, 0x31800000, v219
	v_cmp_gt_f32_e64 s[4:5], s86, v22
	v_mul_f32_e32 v23, 0x4b800000, v22
	s_nop 0
	v_cndmask_b32_e64 v22, v22, v23, s[4:5]
	v_rsq_f32_e32 v22, v22
	s_nop 0
	v_mul_f32_e32 v23, 0x45800000, v22
	v_cndmask_b32_e64 v22, v22, v23, s[4:5]
	v_mul_f32_e32 v22, 0x3db8aa3b, v22
	v_pk_mul_f32 v[16:17], v[16:17], v[22:23] op_sel_hi:[1,0]
	v_pk_mul_f32 v[14:15], v[14:15], v[22:23] op_sel_hi:[1,0]
	v_max_f32_e32 v24, v16, v17
	v_max_f32_e32 v23, v14, v15
	v_max3_f32 v23, v23, s61, v24
	v_pk_mul_f32 v[12:13], v[12:13], v[22:23] op_sel_hi:[1,0]
	v_pk_mul_f32 v[176:177], v[10:11], v[22:23] op_sel_hi:[1,0]
	v_max_f32_e32 v11, v12, v13
	v_max_f32_e32 v10, v176, v177
	v_max3_f32 v23, v23, v10, v11
	v_pk_mul_f32 v[10:11], v[8:9], v[22:23] op_sel_hi:[1,0]
	v_pk_mul_f32 v[182:183], v[6:7], v[22:23] op_sel_hi:[1,0]
	v_max_f32_e32 v7, v10, v11
	v_max_f32_e32 v6, v182, v183
	v_pk_mul_f32 v[180:181], v[4:5], v[22:23] op_sel_hi:[1,0]
	v_pk_mul_f32 v[186:187], v[2:3], v[22:23] op_sel_hi:[1,0]
	v_max3_f32 v6, v23, v6, v7
	v_max_f32_e32 v2, v186, v187
	v_max_f32_e32 v3, v180, v181
	v_max3_f32 v2, v6, v2, v3
	ds_bpermute_b32 v3, v208, v2
	s_waitcnt lgkmcnt(0)
	v_max_f32_e32 v3, v3, v3
	v_max_f32_e32 v2, v2, v3
	ds_bpermute_b32 v3, v209, v2
	s_and_saveexec_b64 s[4:5], vcc
	s_cbranch_execz .LBB0_1003
	s_waitcnt lgkmcnt(0)
	v_max_f32_e32 v3, v3, v3
	v_max_f32_e32 v2, v2, v2
	v_lshl_add_u32 v4, v191, 4, s50
	v_max_f32_e32 v2, v2, v3
	ds_write_b32 v4, v2
